# P0 p->bf16 loop: workgroup-uniform groups of 4 grid-stride items, 8 nt loads in flight per thread with counted waits 6/5/4/3, v_cvt_pk_bf16_f32 packs, remainder falls into the original loop; on top of
# speedup vs baseline: 1.0058x; 1.0058x over previous
; __device__ __forceinline__ unsigned pk2(float lo, float hi) { return f2bf(lo) | (f2bf(hi) << 16); }
; __device__ __forceinline__ void p0_prologue(const Args& a, LAS unsigned char* lds) {
;     ...
;     { const float* p = a.in[1]; bf16* pb = (bf16*)(ws + WS_PB); const size_t n8 = (size_t)2 * M * PLE / 8;
;       for (size_t i = (size_t)blockIdx.x * 512 + tid; i < n8; i += (size_t)G * 512) { const f32x4 v0 = *(const f32x4*)(p + i * 8), v1 = *(const f32x4*)(p + i * 8 + 4);
;           u32x4 w; w.x = pk2(v0[0], v0[1]); w.y = pk2(v0[2], v0[3]); w.z = pk2(v1[0], v1[1]); w.w = pk2(v1[2], v1[3]); *(u32x4*)(pb + i * 8) = w; } }
.LBB0_324:
	s_or_b64 exec, exec, s[8:9]
	s_mov_b32 s3, 0
	s_lshl_b64 s[0:1], s[2:3], 9
	v_mov_b32_e32 v201, 0
	s_waitcnt lgkmcnt(0)
	v_lshl_add_u64 v[2:3], s[0:1], 0, v[200:201]
	s_mov_b64 s[0:1], 0x100000
	v_cmp_gt_u64_e32 vcc, s[0:1], v[2:3]
	s_and_saveexec_b64 s[0:1], vcc
	s_cbranch_execz .LBB0_327
	s_load_dwordx2 s[6:7], s[92:93], 0x8
	v_readlane_b32 s4, v254, 7
	v_readlane_b32 s5, v254, 8
	s_mov_b32 s10, s4
	s_ashr_i32 s11, s4, 31
	s_lshl_b64 s[4:5], s[10:11], 9
	s_lshl_b64 s[8:9], s[2:3], 14
	s_waitcnt lgkmcnt(0)
	s_add_u32 s6, s6, s8
	v_lshlrev_b32_e32 v4, 5, v200
	v_mov_b32_e32 v5, v201
	s_addc_u32 s7, s7, s9
	v_lshl_add_u64 v[4:5], s[6:7], 0, v[4:5]
	s_lshl_b64 s[6:7], s[10:11], 14
	s_lshl_b64 s[8:9], s[2:3], 13
	s_add_u32 s8, s74, s8
	s_waitcnt vmcnt(23)
	v_lshlrev_b32_e32 v6, 4, v200
	v_mov_b32_e32 v7, v201
	s_addc_u32 s9, s75, s9
	v_lshl_add_u64 v[6:7], s[8:9], 0, v[6:7]
	s_mov_b64 s[8:9], 0x1000000
	v_lshl_add_u64 v[6:7], v[6:7], 0, s[8:9]
	s_mov_b32 s8, s10
	v_writelane_b32 v254, s8, 7
	v_lshl_add_u64 v[4:5], v[4:5], 0, 16
	s_movk_i32 s3, 0x7fff
	v_writelane_b32 v254, s9, 8
	s_lshl_b64 s[8:9], s[10:11], 13
	s_mov_b64 s[10:11], 0
	s_mov_b32 s14, 0xffff0000
	s_mov_b64 s[12:13], 0xfffff
	v_readlane_b32 s98, v254, 7
	s_nop 1
	s_mul_i32 s100, s98, 3
	s_add_u32 s100, s100, s2
	s_lshl_b32 s101, s98, 2
	s_lshl_b64 s[98:99], s[4:5], 2
.Lpcv_grp:
	s_cmpk_lt_u32 s100, 0x800
	s_cbranch_scc0 .Lpcv_rest
	v_lshl_add_u64 v[56:57], v[4:5], 0, s[6:7]
	v_lshl_add_u64 v[58:59], v[56:57], 0, s[6:7]
	v_lshl_add_u64 v[60:61], v[58:59], 0, s[6:7]
	global_load_dwordx4 v[24:27], v[4:5], off offset:-16 nt
	global_load_dwordx4 v[28:31], v[4:5], off nt
	global_load_dwordx4 v[32:35], v[56:57], off offset:-16 nt
	global_load_dwordx4 v[36:39], v[56:57], off nt
	global_load_dwordx4 v[40:43], v[58:59], off offset:-16 nt
	global_load_dwordx4 v[44:47], v[58:59], off nt
	global_load_dwordx4 v[48:51], v[60:61], off offset:-16 nt
	global_load_dwordx4 v[52:55], v[60:61], off nt
	v_lshl_add_u64 v[4:5], v[60:61], 0, s[6:7]
	v_lshl_add_u64 v[62:63], v[6:7], 0, s[8:9]
	v_lshl_add_u64 v[64:65], v[62:63], 0, s[8:9]
	v_lshl_add_u64 v[66:67], v[64:65], 0, s[8:9]
	v_lshl_add_u64 v[2:3], v[2:3], 0, s[98:99]
	s_waitcnt vmcnt(6)
	v_cvt_pk_bf16_f32 v24, v24, v25
	v_cvt_pk_bf16_f32 v25, v26, v27
	v_cvt_pk_bf16_f32 v26, v28, v29
	v_cvt_pk_bf16_f32 v27, v30, v31
	global_store_dwordx4 v[6:7], v[24:27], off nt
	s_waitcnt vmcnt(5)
	v_cvt_pk_bf16_f32 v32, v32, v33
	v_cvt_pk_bf16_f32 v33, v34, v35
	v_cvt_pk_bf16_f32 v34, v36, v37
	v_cvt_pk_bf16_f32 v35, v38, v39
	global_store_dwordx4 v[62:63], v[32:35], off nt
	s_waitcnt vmcnt(4)
	v_cvt_pk_bf16_f32 v40, v40, v41
	v_cvt_pk_bf16_f32 v41, v42, v43
	v_cvt_pk_bf16_f32 v42, v44, v45
	v_cvt_pk_bf16_f32 v43, v46, v47
	global_store_dwordx4 v[64:65], v[40:43], off nt
	s_waitcnt vmcnt(3)
	v_cvt_pk_bf16_f32 v48, v48, v49
	v_cvt_pk_bf16_f32 v49, v50, v51
	v_cvt_pk_bf16_f32 v50, v52, v53
	v_cvt_pk_bf16_f32 v51, v54, v55
	global_store_dwordx4 v[66:67], v[48:51], off nt
	v_lshl_add_u64 v[6:7], v[66:67], 0, s[8:9]
	s_add_u32 s100, s100, s101
	s_branch .Lpcv_grp
.Lpcv_rest:
	v_cmp_lt_u64_e32 vcc, s[12:13], v[2:3]
	s_nop 1
	s_andn2_b64 exec, exec, vcc
	s_cbranch_execz .LBB0_327
